# attention loops: packed f32 VALU ops (broadcast pk_mul rescale, pk_add) rewritten as scalar pairs, bit-identical
# baseline (speedup 1.0000x reference)
; template <int MODE>
; __device__ __forceinline__ void attn_pass(LAS unsigned char* lds, const bf16_t* base, int gk, int q0, const float* relb_b, const unsigned* selrow, f32x4 (&o)[2][4]) {
;     ...
;             if (__any(mnew > mrun[qt])) {
; #pragma unroll
;                 for (int dt = 0; dt < 4; ++dt) o[qt][dt] = o[qt][dt] * alpha; }
.LBB0_66:
	v_mul_f32_e32 v30, v30, v2
	v_mul_f32_e32 v31, v31, v2
	v_mul_f32_e32 v28, v28, v2
	v_mul_f32_e32 v29, v29, v2
	v_mul_f32_e32 v26, v26, v2
	v_mul_f32_e32 v27, v27, v2
	v_mul_f32_e32 v24, v24, v2
	v_mul_f32_e32 v25, v25, v2
	v_mul_f32_e32 v34, v34, v2
	v_mul_f32_e32 v35, v35, v2
	v_mul_f32_e32 v32, v32, v2
	v_mul_f32_e32 v33, v33, v2
	v_mul_f32_e32 v38, v38, v2
	v_mul_f32_e32 v39, v39, v2
	v_mul_f32_e32 v36, v36, v2
	v_mul_f32_e32 v37, v37, v2

; template <int MODE>
; __device__ __forceinline__ void attn_pass(LAS unsigned char* lds, const bf16_t* base, int gk, int q0, const float* relb_b, const unsigned* selrow, f32x4 (&o)[2][4]) {
;     ...
;             if (__any(mnew > mrun[qt])) {
; #pragma unroll
;                 for (int dt = 0; dt < 4; ++dt) o[qt][dt] = o[qt][dt] * alpha; }
.LBB0_70:
	v_mul_f32_e32 v10, v10, v96
	v_mul_f32_e32 v11, v11, v96
	v_mul_f32_e32 v8, v8, v96
	v_mul_f32_e32 v9, v9, v96
	v_mul_f32_e32 v14, v14, v96
	v_mul_f32_e32 v15, v15, v96
	v_mul_f32_e32 v12, v12, v96
	v_mul_f32_e32 v13, v13, v96
	v_mul_f32_e32 v18, v18, v96
	v_mul_f32_e32 v19, v19, v96
	v_mul_f32_e32 v16, v16, v96
	v_mul_f32_e32 v17, v17, v96
	v_mul_f32_e32 v22, v22, v96
	v_mul_f32_e32 v23, v23, v96
	v_mul_f32_e32 v20, v20, v96
	v_mul_f32_e32 v21, v21, v96

; template <int MODE>
; __device__ __forceinline__ void attn_pass(LAS unsigned char* lds, const bf16_t* base, int gk, int q0, const float* relb_b, const unsigned* selrow, f32x4 (&o)[2][4]) {
;     ...
;             if (__any(mnew > mrun[qt])) {
; #pragma unroll
;                 for (int dt = 0; dt < 4; ++dt) o[qt][dt] = o[qt][dt] * alpha; }
.LBB0_154:
	v_mul_f32_e32 v70, v70, v2
	v_mul_f32_e32 v71, v71, v2
	v_mul_f32_e32 v68, v68, v2
	v_mul_f32_e32 v69, v69, v2
	v_mul_f32_e32 v66, v66, v2
	v_mul_f32_e32 v67, v67, v2
	v_mul_f32_e32 v64, v64, v2
	v_mul_f32_e32 v65, v65, v2
	v_mul_f32_e32 v62, v62, v2
	v_mul_f32_e32 v63, v63, v2
	v_mul_f32_e32 v60, v60, v2
	v_mul_f32_e32 v61, v61, v2
	v_mul_f32_e32 v58, v58, v2
	v_mul_f32_e32 v59, v59, v2
	v_mul_f32_e32 v56, v56, v2
	v_mul_f32_e32 v57, v57, v2

; template <int MODE>
; __device__ __forceinline__ void attn_pass(LAS unsigned char* lds, const bf16_t* base, int gk, int q0, const float* relb_b, const unsigned* selrow, f32x4 (&o)[2][4]) {
;     ...
;             if (__any(mnew > mrun[qt])) {
; #pragma unroll
;                 for (int dt = 0; dt < 4; ++dt) o[qt][dt] = o[qt][dt] * alpha; }
.LBB0_158:
	v_mul_f32_e32 v54, v54, v128
	v_mul_f32_e32 v55, v55, v128
	v_mul_f32_e32 v52, v52, v128
	v_mul_f32_e32 v53, v53, v128
	v_mul_f32_e32 v50, v50, v128
	v_mul_f32_e32 v51, v51, v128
	v_mul_f32_e32 v48, v48, v128
	v_mul_f32_e32 v49, v49, v128
	v_mul_f32_e32 v46, v46, v128
	v_mul_f32_e32 v47, v47, v128
	v_mul_f32_e32 v44, v44, v128
	v_mul_f32_e32 v45, v45, v128
	v_mul_f32_e32 v42, v42, v128
	v_mul_f32_e32 v43, v43, v128
	v_mul_f32_e32 v40, v40, v128
	v_mul_f32_e32 v41, v41, v128

; template <int MODE>
; __device__ __forceinline__ void attn_wave(LAS unsigned char* lds, const bf16_t* qkv, bf16_t* Yout, const float* sinks, int wi) {
;     ...
;                 mx = fmaxf(mx, __shfl_xor(mx, 16)); mx = fmaxf(mx, __shfl_xor(mx, 32));
;                 const float mnew = fmaxf(mrun[qt], mx); const float alpha = __builtin_amdgcn_exp2f(mrun[qt] - mnew); mrun[qt] = mnew;
;                 float ps = 0.f;
; #pragma unroll
;                 for (int nt = 0; nt < 2; ++nt)
; #pragma unroll
;                     for (int j = 0; j < 4; ++j) { const float p = __builtin_amdgcn_exp2f(s[nt][j] - mnew); s[nt][j] = p; ps += p; }
;                 lrun[qt] = lrun[qt] * alpha + ps;
; #pragma unroll
;                 for (int dt = 0; dt < 4; ++dt) o[qt][dt] = o[qt][dt] * alpha;
;             } else {
;                 float lk[2][4], c4[2];
; #pragma unroll
;                 for (int nt = 0; nt < 2; ++nt) { c4[nt] = 0.f;
; #pragma unroll
;                     for (int j = 0; j < 4; ++j) { const bool valid = (dbase - (16 * nt + j)) > 0; const float z = s[nt][j] * C1;
;                         const float e = __builtin_amdgcn_exp2f(-fabsf(z));
;                         const float sp = fmaxf(z, 0.f) + __builtin_amdgcn_logf(1.f + e);
;                         lk[nt][j] = valid ? -sp : 0.f; s[nt][j] = valid ? (z - sp) : -1e30f; c4[nt] += lk[nt][j]; } }
;                 float after = 0.f;
; #pragma unroll
;     ...
;                     const float v1 = __shfl_xor(c4[nt], 16), v2 = __shfl_xor(c4[nt], 32), v3 = __shfl_xor(c4[nt], 48);
;                     const float G = (((g ^ 1) > g) ? v1 : 0.f) + (((g ^ 2) > g) ? v2 : 0.f) + (((g ^ 3) > g) ? v3 : 0.f);
;                     const float T = c4[nt] + v1 + v2 + v3;
;                     float sfx = carry[qt] + after + G;
; #pragma unroll
;                     for (int j = 3; j >= 0; --j) { const float w = __builtin_amdgcn_exp2f(s[nt][j] + sfx); s[nt][j] = w; sfx += lk[nt][j]; }
;                     after += T;
;                 }
;                 carry[qt] += after;
;             }
;             u32x4 w; w.x = cvtpk(s[0][0], s[0][1]); w.y = cvtpk(s[0][2], s[0][3]); w.z = cvtpk(s[1][0], s[1][1]); w.w = cvtpk(s[1][2], s[1][3]);
;             const bf16x8 pb = __builtin_bit_cast(bf16x8, w);
; #pragma unroll
;             for (int dt = 0; dt < 4; ++dt) o[qt][dt] = MFMA16(vfr[dt], pb, o[qt][dt]);
.LBB0_258:
	s_or_b64 exec, exec, s[4:5]
	s_mov_b32 s4, 0xf149f2ca
	v_max3_f32 v122, v133, s4, v132
	v_max3_f32 v122, v122, v125, v124
	v_cmp_lt_i32_e32 vcc, v223, v218
	v_max3_f32 v122, v122, v127, v126
	v_max3_f32 v122, v122, v121, v120
	v_cndmask_b32_e32 v123, v217, v223, vcc
	v_lshlrev_b32_e32 v123, 2, v123
	ds_bpermute_b32 v123, v123, v122
	v_cmp_lt_i32_e32 vcc, v224, v218
	s_waitcnt lgkmcnt(0)
	v_max_f32_e32 v123, v123, v123
	v_max_f32_e32 v122, v122, v123
	v_cndmask_b32_e32 v123, v217, v224, vcc
	v_lshlrev_b32_e32 v123, 2, v123
	ds_bpermute_b32 v123, v123, v122
	s_waitcnt lgkmcnt(0)
	v_max3_f32 v128, v157, v122, v123
	v_sub_f32_e32 v123, v133, v128
	v_exp_f32_e32 v123, v123
	v_sub_f32_e32 v130, v132, v128
	v_exp_f32_e32 v130, v130
	v_sub_f32_e32 v125, v125, v128
	v_exp_f32_e32 v125, v125
	v_sub_f32_e32 v124, v124, v128
	v_exp_f32_e32 v124, v124
	v_sub_f32_e32 v127, v127, v128
	v_add_f32_e32 v129, 0, v123
	v_exp_f32_e32 v127, v127
	v_sub_f32_e32 v126, v126, v128
	v_add_f32_e32 v129, v130, v129
	v_exp_f32_e32 v126, v126
	v_sub_f32_e32 v121, v121, v128
	v_add_f32_e32 v129, v125, v129
	v_exp_f32_e32 v131, v121
	v_add_f32_e32 v129, v124, v129
	v_add_f32_e32 v129, v127, v129
	v_add_f32_e32 v129, v126, v129
	v_sub_f32_e32 v120, v120, v128
	v_sub_f32_e32 v122, v157, v128
	v_add_f32_e32 v121, v131, v129
	v_exp_f32_e32 v129, v120
	v_exp_f32_e32 v120, v122
	v_cvt_pk_bf16_f32 v122, v127, v126
	v_mov_b32_e32 v157, v128
	v_add_f32_e32 v132, v129, v121
	v_fmac_f32_e32 v132, v156, v120
	v_mul_f32_e32 v10, v10, v120
	v_mul_f32_e32 v11, v11, v120
	v_mul_f32_e32 v8, v8, v120
	v_mul_f32_e32 v9, v9, v120
	v_mul_f32_e32 v14, v14, v120
	v_mul_f32_e32 v15, v15, v120
	v_mul_f32_e32 v12, v12, v120
	v_mul_f32_e32 v13, v13, v120
	v_mul_f32_e32 v18, v18, v120
	v_mul_f32_e32 v19, v19, v120
	v_mul_f32_e32 v16, v16, v120
	v_mul_f32_e32 v17, v17, v120
	v_mul_f32_e32 v22, v22, v120
	v_mul_f32_e32 v23, v23, v120
	v_mul_f32_e32 v20, v20, v120
	v_mul_f32_e32 v21, v21, v120
	v_cvt_pk_bf16_f32 v120, v123, v130
	v_cvt_pk_bf16_f32 v121, v125, v124
	v_cvt_pk_bf16_f32 v123, v131, v129
	v_mov_b32_e32 v156, v132
	s_nop 0
	v_mfma_f32_16x16x32_bf16 v[8:11], v[116:119], v[120:123], v[8:11]
	v_mfma_f32_16x16x32_bf16 v[12:15], v[112:115], v[120:123], v[12:15]
	v_mfma_f32_16x16x32_bf16 v[16:19], v[108:111], v[120:123], v[16:19]
	v_mfma_f32_16x16x32_bf16 v[20:23], v[104:107], v[120:123], v[20:23]

; #define MFMA16(a, b, c) __builtin_amdgcn_mfma_f32_16x16x32_bf16((a), (b), (c), 0, 0, 0)
; template <int MODE>
; __device__ __forceinline__ void attn_wave(LAS unsigned char* lds, const bf16_t* qkv, bf16_t* Yout, const float* sinks, int wi) {
;     ...
;             f32x4 s[2];
; #pragma unroll
;             for (int nt = 0; nt < 2; ++nt) { f32x4 z = (f32x4){0.f, 0.f, 0.f, 0.f}; z = MFMA16(kf[nt][0], qf[qt][0], z); s[nt] = MFMA16(kf[nt][1], qf[qt][1], z); }
;             const int dbase = q0 + QSTEP * qt + c - k0 - 4 * g;
;             if (MODE == MODE_A) {
;                 float mx = -1e30f;
; #pragma unroll
;                 for (int nt = 0; nt < 2; ++nt)
; #pragma unroll
;                     for (int j = 0; j < 4; ++j) { const int dist = dbase - (16 * nt + j); const bool valid = (unsigned)dist < 128u;
;                         const float bias2 = lutp[qt * HSTEP * 128 + (dist & 127)];
;                         const float lg = valid ? (s[nt][j] * C1 + bias2) : -1e30f; s[nt][j] = lg; mx = fmaxf(mx, lg); }
;                 mx = fmaxf(mx, __shfl_xor(mx, 16)); mx = fmaxf(mx, __shfl_xor(mx, 32));
;                 const float mnew = fmaxf(mrun[qt], mx); const float alpha = __builtin_amdgcn_exp2f(mrun[qt] - mnew); mrun[qt] = mnew;
;                 float ps = 0.f;
; #pragma unroll
;                 for (int nt = 0; nt < 2; ++nt)
; #pragma unroll
;                     for (int j = 0; j < 4; ++j) { const float p = __builtin_amdgcn_exp2f(s[nt][j] - mnew); s[nt][j] = p; ps += p; }
;                 lrun[qt] = lrun[qt] * alpha + ps;
; #pragma unroll
;                 for (int dt = 0; dt < 4; ++dt) o[qt][dt] = o[qt][dt] * alpha;
;             } else {
;                 float lk[2][4], c4[2];
; #pragma unroll
;                 for (int nt = 0; nt < 2; ++nt) { c4[nt] = 0.f;
; #pragma unroll
;                     for (int j = 0; j < 4; ++j) { const bool valid = (dbase - (16 * nt + j)) > 0; const float z = s[nt][j] * C1;
;                         const float e = __builtin_amdgcn_exp2f(-fabsf(z));
;                         const float sp = fmaxf(z, 0.f) + __builtin_amdgcn_logf(1.f + e);
;                         lk[nt][j] = valid ? -sp : 0.f; s[nt][j] = valid ? (z - sp) : -1e30f; c4[nt] += lk[nt][j]; } }
;                 float after = 0.f;
; #pragma unroll
;     ...
;                     const float v1 = __shfl_xor(c4[nt], 16), v2 = __shfl_xor(c4[nt], 32), v3 = __shfl_xor(c4[nt], 48);
.LBB0_264:
	s_waitcnt vmcnt(3)
	v_mfma_f32_16x16x32_bf16 v[136:139], v[120:123], v[72:75], 0
	s_waitcnt vmcnt(2)
	v_mfma_f32_16x16x32_bf16 v[140:143], v[124:127], v[76:79], v[136:139]
	s_waitcnt vmcnt(1)
	v_mfma_f32_16x16x32_bf16 v[136:139], v[132:135], v[72:75], 0
	s_waitcnt vmcnt(0)
	v_mfma_f32_16x16x32_bf16 v[136:139], v[128:131], v[76:79], v[136:139]
	v_add_u32_e32 v228, s19, v167
	v_add_u32_e32 v228, 0x12000, v228
	ds_read_b32 v228, v228
	v_add_u32_e32 v229, s19, v165
	v_add_u32_e32 v229, 0x11ffc, v229
	ds_read_b32 v229, v229
	v_add_u32_e32 v230, s19, v165
	v_add_u32_e32 v230, 0x11ff8, v230
	ds_read_b32 v230, v230
	v_add_u32_e32 v231, s19, v165
	v_add_u32_e32 v231, 0x11ff4, v231
	ds_read_b32 v231, v231
	v_add_u32_e32 v232, s19, v165
	v_add_u32_e32 v232, 0x11fc0, v232
	ds_read_b32 v232, v232
	v_add_u32_e32 v233, s19, v165
	v_add_u32_e32 v233, 0x11fbc, v233
	ds_read_b32 v233, v233
	v_add_u32_e32 v234, s19, v165
	v_add_u32_e32 v234, 0x11fb8, v234
	ds_read_b32 v234, v234
	v_add_u32_e32 v235, s19, v165
	v_add_u32_e32 v235, 0x11fb4, v235
	ds_read_b32 v235, v235
	s_waitcnt lgkmcnt(0)
	v_cmp_gt_u32_e32 vcc, s15, v171
	v_fmac_f32_e32 v228, 0x3e38aa3b, v140
	s_nop 0
	v_cndmask_b32_e32 v173, v226, v228, vcc
	v_add_u32_e32 v236, 30, v170
	v_cmp_gt_u32_e32 vcc, s15, v236
	v_fmac_f32_e32 v229, 0x3e38aa3b, v141
	s_nop 0
	v_cndmask_b32_e32 v172, v226, v229, vcc
	v_add_u32_e32 v236, 29, v170
	v_cmp_gt_u32_e32 vcc, s15, v236
	v_fmac_f32_e32 v230, 0x3e38aa3b, v142
	s_nop 0
	v_cndmask_b32_e32 v141, v226, v230, vcc
	v_add_u32_e32 v236, 28, v170
	v_cmp_gt_u32_e32 vcc, s15, v236
	v_fmac_f32_e32 v231, 0x3e38aa3b, v143
	s_nop 0
	v_cndmask_b32_e32 v140, v226, v231, vcc
	v_add_u32_e32 v236, 15, v170
	v_cmp_gt_u32_e32 vcc, s15, v236
	v_fmac_f32_e32 v232, 0x3e38aa3b, v136
	s_nop 0
	v_cndmask_b32_e32 v143, v226, v232, vcc
	v_add_u32_e32 v236, 14, v170
	v_cmp_gt_u32_e32 vcc, s15, v236
	v_fmac_f32_e32 v233, 0x3e38aa3b, v137
	s_nop 0
	v_cndmask_b32_e32 v142, v226, v233, vcc
	v_add_u32_e32 v236, 13, v170
	v_cmp_gt_u32_e32 vcc, s15, v236
	v_fmac_f32_e32 v234, 0x3e38aa3b, v138
	s_nop 0
	v_cndmask_b32_e32 v137, v226, v234, vcc
	v_add_u32_e32 v236, 12, v170
	v_cmp_gt_u32_e32 vcc, s15, v236
	v_fmac_f32_e32 v235, 0x3e38aa3b, v139
	s_nop 0
	v_cndmask_b32_e32 v136, v226, v235, vcc
	v_max3_f32 v138, v173, s86, v172
	v_max3_f32 v138, v138, v141, v140
	v_cmp_lt_i32_e32 vcc, v223, v218
	v_max3_f32 v138, v138, v143, v142
	v_max3_f32 v138, v138, v137, v136
	v_cndmask_b32_e32 v139, v217, v223, vcc
	v_lshlrev_b32_e32 v139, 2, v139
	ds_bpermute_b32 v139, v139, v138
	v_cmp_lt_i32_e32 vcc, v224, v218
	s_waitcnt lgkmcnt(0)
	v_max_f32_e32 v139, v139, v139
	v_max_f32_e32 v138, v138, v139
	v_cndmask_b32_e32 v139, v217, v224, vcc
	v_lshlrev_b32_e32 v139, 2, v139
	ds_bpermute_b32 v139, v139, v138
	s_waitcnt lgkmcnt(0)
	v_max3_f32 v174, v163, v138, v139
	v_sub_f32_e32 v139, v173, v174
	v_exp_f32_e32 v139, v139
	v_sub_f32_e32 v172, v172, v174
	v_exp_f32_e32 v172, v172
	v_sub_f32_e32 v141, v141, v174
	v_exp_f32_e32 v141, v141
	v_sub_f32_e32 v140, v140, v174
	v_exp_f32_e32 v140, v140
	v_sub_f32_e32 v143, v143, v174
	v_sub_f32_e32 v138, v163, v174
	v_add_f32_e32 v163, 0, v139
	v_exp_f32_e32 v143, v143
	v_sub_f32_e32 v142, v142, v174
	v_add_f32_e32 v163, v172, v163
	v_exp_f32_e32 v142, v142
	v_sub_f32_e32 v137, v137, v174
	v_add_f32_e32 v163, v141, v163
	v_exp_f32_e32 v173, v137
	v_add_f32_e32 v163, v140, v163
	v_add_f32_e32 v163, v143, v163
	v_add_f32_e32 v163, v142, v163
	v_sub_f32_e32 v136, v136, v174
	v_add_f32_e32 v137, v173, v163
	v_exp_f32_e32 v163, v136
	v_exp_f32_e32 v136, v138
	v_cvt_pk_bf16_f32 v138, v143, v142
	v_add_f32_e32 v175, v163, v137
	v_fmac_f32_e32 v175, v164, v136
	v_mul_f32_e32 v58, v58, v136
	v_mul_f32_e32 v59, v59, v136
	v_mul_f32_e32 v56, v56, v136
	v_mul_f32_e32 v57, v57, v136
	v_mul_f32_e32 v62, v62, v136
	v_mul_f32_e32 v63, v63, v136
	v_mul_f32_e32 v60, v60, v136
	v_mul_f32_e32 v61, v61, v136
	v_mul_f32_e32 v66, v66, v136
	v_mul_f32_e32 v67, v67, v136
	v_mul_f32_e32 v64, v64, v136
	v_mul_f32_e32 v65, v65, v136
	v_mul_f32_e32 v70, v70, v136
	v_mul_f32_e32 v71, v71, v136
	v_mul_f32_e32 v68, v68, v136
	v_mul_f32_e32 v69, v69, v136
	v_cvt_pk_bf16_f32 v136, v139, v172
	v_cvt_pk_bf16_f32 v137, v141, v140
	v_cvt_pk_bf16_f32 v139, v173, v163
	v_mov_b32_e32 v164, v175
	v_mov_b32_e32 v163, v174
	v_mfma_f32_16x16x32_bf16 v[56:59], v[116:119], v[136:139], v[56:59]
	v_mfma_f32_16x16x32_bf16 v[60:63], v[112:115], v[136:139], v[60:63]
	v_mfma_f32_16x16x32_bf16 v[64:67], v[108:111], v[136:139], v[64:67]
	v_mfma_f32_16x16x32_bf16 v[68:71], v[104:107], v[136:139], v[68:71]
	s_and_b64 vcc, exec, s[4:5]
	s_cbranch_vccnz .LBB0_262
; #define MFMA16(a, b, c) __builtin_amdgcn_mfma_f32_16x16x32_bf16((a), (b), (c), 0, 0, 0)
; template <int MODE>
; __device__ __forceinline__ void attn_wave(LAS unsigned char* lds, const bf16_t* qkv, bf16_t* Yout, const float* sinks, int wi) {
;     ...
;             f32x4 s[2];
; #pragma unroll
;             for (int nt = 0; nt < 2; ++nt) { f32x4 z = (f32x4){0.f, 0.f, 0.f, 0.f}; z = MFMA16(kf[nt][0], qf[qt][0], z); s[nt] = MFMA16(kf[nt][1], qf[qt][1], z); }
;             const int dbase = q0 + QSTEP * qt + c - k0 - 4 * g;
;             if (MODE == MODE_A) {
;                 float mx = -1e30f;
; #pragma unroll
;                 for (int nt = 0; nt < 2; ++nt)
; #pragma unroll
;                     for (int j = 0; j < 4; ++j) { const int dist = dbase - (16 * nt + j); const bool valid = (unsigned)dist < 128u;
;                         const float bias2 = lutp[qt * HSTEP * 128 + (dist & 127)];
;                         const float lg = valid ? (s[nt][j] * C1 + bias2) : -1e30f; s[nt][j] = lg; mx = fmaxf(mx, lg); }
;                 mx = fmaxf(mx, __shfl_xor(mx, 16)); mx = fmaxf(mx, __shfl_xor(mx, 32));
;                 const float mnew = fmaxf(mrun[qt], mx); const float alpha = __builtin_amdgcn_exp2f(mrun[qt] - mnew); mrun[qt] = mnew;
;                 float ps = 0.f;
; #pragma unroll
;                 for (int nt = 0; nt < 2; ++nt)
; #pragma unroll
;                     for (int j = 0; j < 4; ++j) { const float p = __builtin_amdgcn_exp2f(s[nt][j] - mnew); s[nt][j] = p; ps += p; }
;                 lrun[qt] = lrun[qt] * alpha + ps;
; #pragma unroll
;                 for (int dt = 0; dt < 4; ++dt) o[qt][dt] = o[qt][dt] * alpha;
;             } else {
;                 float lk[2][4], c4[2];
; #pragma unroll
;                 for (int nt = 0; nt < 2; ++nt) { c4[nt] = 0.f;
; #pragma unroll
;                     for (int j = 0; j < 4; ++j) { const bool valid = (dbase - (16 * nt + j)) > 0; const float z = s[nt][j] * C1;
;                         const float e = __builtin_amdgcn_exp2f(-fabsf(z));
;                         const float sp = fmaxf(z, 0.f) + __builtin_amdgcn_logf(1.f + e);
;                         lk[nt][j] = valid ? -sp : 0.f; s[nt][j] = valid ? (z - sp) : -1e30f; c4[nt] += lk[nt][j]; } }
;                 float after = 0.f;
; #pragma unroll
;     ...
;                     const float v1 = __shfl_xor(c4[nt], 16), v2 = __shfl_xor(c4[nt], 32), v3 = __shfl_xor(c4[nt], 48);
.LBB0_281:
	s_waitcnt vmcnt(3)
	v_mfma_f32_16x16x32_bf16 v[136:139], v[120:123], v[80:83], 0
	s_waitcnt vmcnt(2)
	v_mfma_f32_16x16x32_bf16 v[140:143], v[124:127], v[84:87], v[136:139]
	s_waitcnt vmcnt(1)
	v_mfma_f32_16x16x32_bf16 v[136:139], v[132:135], v[80:83], 0
	s_waitcnt vmcnt(0)
	v_mfma_f32_16x16x32_bf16 v[136:139], v[128:131], v[84:87], v[136:139]
	v_add_u32_e32 v228, s19, v167
	v_add_u32_e32 v228, 0x12200, v228
	ds_read_b32 v228, v228
	v_add_u32_e32 v229, s19, v167
	v_add_u32_e32 v229, 0x121fc, v229
	ds_read_b32 v229, v229
	v_add_u32_e32 v230, s19, v167
	v_add_u32_e32 v230, 0x121f8, v230
	ds_read_b32 v230, v230
	v_add_u32_e32 v231, s19, v167
	v_add_u32_e32 v231, 0x121f4, v231
	ds_read_b32 v231, v231
	v_add_u32_e32 v232, s19, v167
	v_add_u32_e32 v232, 0x121c0, v232
	ds_read_b32 v232, v232
	v_add_u32_e32 v233, s19, v165
	v_add_u32_e32 v233, 0x121bc, v233
	ds_read_b32 v233, v233
	v_add_u32_e32 v234, s19, v165
	v_add_u32_e32 v234, 0x121b8, v234
	ds_read_b32 v234, v234
	v_add_u32_e32 v235, s19, v165
	v_add_u32_e32 v235, 0x121b4, v235
	ds_read_b32 v235, v235
	s_waitcnt lgkmcnt(0)
	v_cmp_gt_u32_e32 vcc, s15, v171
	v_fmac_f32_e32 v228, 0x3e38aa3b, v140
	s_nop 0
	v_cndmask_b32_e32 v173, v226, v228, vcc
	v_add_u32_e32 v236, 30, v170
	v_cmp_gt_u32_e32 vcc, s15, v236
	v_fmac_f32_e32 v229, 0x3e38aa3b, v141
	s_nop 0
	v_cndmask_b32_e32 v172, v226, v229, vcc
	v_add_u32_e32 v236, 29, v170
	v_cmp_gt_u32_e32 vcc, s15, v236
	v_fmac_f32_e32 v230, 0x3e38aa3b, v142
	s_nop 0
	v_cndmask_b32_e32 v141, v226, v230, vcc
	v_add_u32_e32 v236, 28, v170
	v_cmp_gt_u32_e32 vcc, s15, v236
	v_fmac_f32_e32 v231, 0x3e38aa3b, v143
	s_nop 0
	v_cndmask_b32_e32 v140, v226, v231, vcc
	v_add_u32_e32 v236, 15, v170
	v_cmp_gt_u32_e32 vcc, s15, v236
	v_fmac_f32_e32 v232, 0x3e38aa3b, v136
	s_nop 0
	v_cndmask_b32_e32 v143, v226, v232, vcc
	v_add_u32_e32 v236, 14, v170
	v_cmp_gt_u32_e32 vcc, s15, v236
	v_fmac_f32_e32 v233, 0x3e38aa3b, v137
	s_nop 0
	v_cndmask_b32_e32 v142, v226, v233, vcc
	v_add_u32_e32 v236, 13, v170
	v_cmp_gt_u32_e32 vcc, s15, v236
	v_fmac_f32_e32 v234, 0x3e38aa3b, v138
	s_nop 0
	v_cndmask_b32_e32 v137, v226, v234, vcc
	v_add_u32_e32 v236, 12, v170
	v_cmp_gt_u32_e32 vcc, s15, v236
	v_fmac_f32_e32 v235, 0x3e38aa3b, v139
	s_nop 0
	v_cndmask_b32_e32 v136, v226, v235, vcc
	v_max3_f32 v138, v173, s86, v172
	v_max3_f32 v138, v138, v141, v140
	v_cmp_lt_i32_e32 vcc, v223, v218
	v_max3_f32 v138, v138, v143, v142
	v_max3_f32 v138, v138, v137, v136
	v_cndmask_b32_e32 v139, v217, v223, vcc
	v_lshlrev_b32_e32 v139, 2, v139
	ds_bpermute_b32 v139, v139, v138
	v_cmp_lt_i32_e32 vcc, v224, v218
	s_waitcnt lgkmcnt(0)
	v_max_f32_e32 v139, v139, v139
	v_max_f32_e32 v138, v138, v139
	v_cndmask_b32_e32 v139, v217, v224, vcc
	v_lshlrev_b32_e32 v139, 2, v139
	ds_bpermute_b32 v139, v139, v138
	s_waitcnt lgkmcnt(0)
	v_max3_f32 v174, v162, v138, v139
	v_sub_f32_e32 v139, v173, v174
	v_exp_f32_e32 v139, v139
	v_sub_f32_e32 v172, v172, v174
	v_exp_f32_e32 v172, v172
	v_sub_f32_e32 v141, v141, v174
	v_exp_f32_e32 v141, v141
	v_sub_f32_e32 v140, v140, v174
	v_exp_f32_e32 v140, v140
	v_sub_f32_e32 v143, v143, v174
	v_sub_f32_e32 v138, v162, v174
	v_add_f32_e32 v162, 0, v139
	v_exp_f32_e32 v143, v143
	v_sub_f32_e32 v142, v142, v174
	v_add_f32_e32 v162, v172, v162
	v_exp_f32_e32 v142, v142
	v_sub_f32_e32 v137, v137, v174
	v_add_f32_e32 v162, v141, v162
	v_exp_f32_e32 v173, v137
	v_add_f32_e32 v162, v140, v162
	v_add_f32_e32 v162, v143, v162
	v_add_f32_e32 v162, v142, v162
	v_sub_f32_e32 v136, v136, v174
	v_add_f32_e32 v137, v173, v162
	v_exp_f32_e32 v162, v136
	v_exp_f32_e32 v136, v138
	v_cvt_pk_bf16_f32 v138, v143, v142
	v_add_f32_e32 v175, v162, v137
	v_fmac_f32_e32 v175, v161, v136
	v_mul_f32_e32 v42, v42, v136
	v_mul_f32_e32 v43, v43, v136
	v_mul_f32_e32 v40, v40, v136
	v_mul_f32_e32 v41, v41, v136
	v_mul_f32_e32 v46, v46, v136
	v_mul_f32_e32 v47, v47, v136
	v_mul_f32_e32 v44, v44, v136
	v_mul_f32_e32 v45, v45, v136
	v_mul_f32_e32 v50, v50, v136
	v_mul_f32_e32 v51, v51, v136
	v_mul_f32_e32 v48, v48, v136
	v_mul_f32_e32 v49, v49, v136
	v_mul_f32_e32 v54, v54, v136
	v_mul_f32_e32 v55, v55, v136
	v_mul_f32_e32 v52, v52, v136
	v_mul_f32_e32 v53, v53, v136
	v_cvt_pk_bf16_f32 v136, v139, v172
	v_cvt_pk_bf16_f32 v137, v141, v140
	v_cvt_pk_bf16_f32 v139, v173, v162
	v_mov_b32_e32 v161, v175
	v_mov_b32_e32 v162, v174
	v_mfma_f32_16x16x32_bf16 v[40:43], v[116:119], v[136:139], v[40:43]
	v_mfma_f32_16x16x32_bf16 v[44:47], v[112:115], v[136:139], v[44:47]
	v_mfma_f32_16x16x32_bf16 v[48:51], v[108:111], v[136:139], v[48:51]
	v_mfma_f32_16x16x32_bf16 v[52:55], v[104:107], v[136:139], v[52:55]
	s_and_b64 vcc, exec, s[4:5]
	s_cbranch_vccnz .LBB0_263
; #define MFMA16(a, b, c) __builtin_amdgcn_mfma_f32_16x16x32_bf16((a), (b), (c), 0, 0, 0)
; template <int MODE>
; __device__ __forceinline__ void attn_wave(LAS unsigned char* lds, const bf16_t* qkv, bf16_t* Yout, const float* sinks, int wi) {
;     ...
;             f32x4 s[2];
; #pragma unroll
;             for (int nt = 0; nt < 2; ++nt) { f32x4 z = (f32x4){0.f, 0.f, 0.f, 0.f}; z = MFMA16(kf[nt][0], qf[qt][0], z); s[nt] = MFMA16(kf[nt][1], qf[qt][1], z); }
;             const int dbase = q0 + QSTEP * qt + c - k0 - 4 * g;
;             if (MODE == MODE_A) {
;                 float mx = -1e30f;
; #pragma unroll
;                 for (int nt = 0; nt < 2; ++nt)
; #pragma unroll
;                     for (int j = 0; j < 4; ++j) { const int dist = dbase - (16 * nt + j); const bool valid = (unsigned)dist < 128u;
;                         const float bias2 = lutp[qt * HSTEP * 128 + (dist & 127)];
;                         const float lg = valid ? (s[nt][j] * C1 + bias2) : -1e30f; s[nt][j] = lg; mx = fmaxf(mx, lg); }
;                 mx = fmaxf(mx, __shfl_xor(mx, 16)); mx = fmaxf(mx, __shfl_xor(mx, 32));
;                 const float mnew = fmaxf(mrun[qt], mx); const float alpha = __builtin_amdgcn_exp2f(mrun[qt] - mnew); mrun[qt] = mnew;
;                 float ps = 0.f;
; #pragma unroll
;                 for (int nt = 0; nt < 2; ++nt)
; #pragma unroll
;                     for (int j = 0; j < 4; ++j) { const float p = __builtin_amdgcn_exp2f(s[nt][j] - mnew); s[nt][j] = p; ps += p; }
;                 lrun[qt] = lrun[qt] * alpha + ps;
; #pragma unroll
;                 for (int dt = 0; dt < 4; ++dt) o[qt][dt] = o[qt][dt] * alpha;
;             } else {
;                 float lk[2][4], c4[2];
; #pragma unroll
;                 for (int nt = 0; nt < 2; ++nt) { c4[nt] = 0.f;
; #pragma unroll
;                     for (int j = 0; j < 4; ++j) { const bool valid = (dbase - (16 * nt + j)) > 0; const float z = s[nt][j] * C1;
;                         const float e = __builtin_amdgcn_exp2f(-fabsf(z));
;                         const float sp = fmaxf(z, 0.f) + __builtin_amdgcn_logf(1.f + e);
;                         lk[nt][j] = valid ? -sp : 0.f; s[nt][j] = valid ? (z - sp) : -1e30f; c4[nt] += lk[nt][j]; } }
;                 float after = 0.f;
; #pragma unroll
;     ...
;                     const float v1 = __shfl_xor(c4[nt], 16), v2 = __shfl_xor(c4[nt], 32), v3 = __shfl_xor(c4[nt], 48);
.LBB0_298:
	s_waitcnt vmcnt(3)
	v_mfma_f32_16x16x32_bf16 v[136:139], v[120:123], v[88:91], 0
	s_waitcnt vmcnt(2)
	v_mfma_f32_16x16x32_bf16 v[140:143], v[124:127], v[92:95], v[136:139]
	s_waitcnt vmcnt(1)
	v_mfma_f32_16x16x32_bf16 v[136:139], v[132:135], v[88:91], 0
	s_waitcnt vmcnt(0)
	v_mfma_f32_16x16x32_bf16 v[136:139], v[128:131], v[92:95], v[136:139]
	v_add_u32_e32 v228, s19, v167
	v_add_u32_e32 v228, 0x12400, v228
	ds_read_b32 v228, v228
	v_add_u32_e32 v229, s19, v167
	v_add_u32_e32 v229, 0x123fc, v229
	ds_read_b32 v229, v229
	v_add_u32_e32 v230, s19, v167
	v_add_u32_e32 v230, 0x123f8, v230
	ds_read_b32 v230, v230
	v_add_u32_e32 v231, s19, v167
	v_add_u32_e32 v231, 0x123f4, v231
	ds_read_b32 v231, v231
	v_add_u32_e32 v232, s19, v167
	v_add_u32_e32 v232, 0x123c0, v232
	ds_read_b32 v232, v232
	v_add_u32_e32 v233, s19, v165
	v_add_u32_e32 v233, 0x123bc, v233
	ds_read_b32 v233, v233
	v_add_u32_e32 v234, s19, v165
	v_add_u32_e32 v234, 0x123b8, v234
	ds_read_b32 v234, v234
	v_add_u32_e32 v235, s19, v165
	v_add_u32_e32 v235, 0x123b4, v235
	ds_read_b32 v235, v235
	s_waitcnt lgkmcnt(0)
	v_cmp_gt_u32_e32 vcc, s15, v171
	v_fmac_f32_e32 v228, 0x3e38aa3b, v140
	s_nop 0
	v_cndmask_b32_e32 v173, v226, v228, vcc
	v_add_u32_e32 v236, 30, v170
	v_cmp_gt_u32_e32 vcc, s15, v236
	v_fmac_f32_e32 v229, 0x3e38aa3b, v141
	s_nop 0
	v_cndmask_b32_e32 v172, v226, v229, vcc
	v_add_u32_e32 v236, 29, v170
	v_cmp_gt_u32_e32 vcc, s15, v236
	v_fmac_f32_e32 v230, 0x3e38aa3b, v142
	s_nop 0
	v_cndmask_b32_e32 v141, v226, v230, vcc
	v_add_u32_e32 v236, 28, v170
	v_cmp_gt_u32_e32 vcc, s15, v236
	v_fmac_f32_e32 v231, 0x3e38aa3b, v143
	s_nop 0
	v_cndmask_b32_e32 v140, v226, v231, vcc
	v_add_u32_e32 v236, 15, v170
	v_cmp_gt_u32_e32 vcc, s15, v236
	v_fmac_f32_e32 v232, 0x3e38aa3b, v136
	s_nop 0
	v_cndmask_b32_e32 v143, v226, v232, vcc
	v_add_u32_e32 v236, 14, v170
	v_cmp_gt_u32_e32 vcc, s15, v236
	v_fmac_f32_e32 v233, 0x3e38aa3b, v137
	s_nop 0
	v_cndmask_b32_e32 v142, v226, v233, vcc
	v_add_u32_e32 v236, 13, v170
	v_cmp_gt_u32_e32 vcc, s15, v236
	v_fmac_f32_e32 v234, 0x3e38aa3b, v138
	s_nop 0
	v_cndmask_b32_e32 v137, v226, v234, vcc
	v_add_u32_e32 v236, 12, v170
	v_cmp_gt_u32_e32 vcc, s15, v236
	v_fmac_f32_e32 v235, 0x3e38aa3b, v139
	s_nop 0
	v_cndmask_b32_e32 v136, v226, v235, vcc
	v_max3_f32 v138, v173, s86, v172
	v_max3_f32 v138, v138, v141, v140
	v_cmp_lt_i32_e32 vcc, v223, v218
	v_max3_f32 v138, v138, v143, v142
	v_max3_f32 v138, v138, v137, v136
	v_cndmask_b32_e32 v139, v217, v223, vcc
	v_lshlrev_b32_e32 v139, 2, v139
	ds_bpermute_b32 v139, v139, v138
	v_cmp_lt_i32_e32 vcc, v224, v218
	s_waitcnt lgkmcnt(0)
	v_max_f32_e32 v139, v139, v139
	v_max_f32_e32 v138, v138, v139
	v_cndmask_b32_e32 v139, v217, v224, vcc
	v_lshlrev_b32_e32 v139, 2, v139
	ds_bpermute_b32 v139, v139, v138
	s_waitcnt lgkmcnt(0)
	v_max3_f32 v174, v159, v138, v139
	v_sub_f32_e32 v139, v173, v174
	v_exp_f32_e32 v139, v139
	v_sub_f32_e32 v172, v172, v174
	v_exp_f32_e32 v172, v172
	v_sub_f32_e32 v141, v141, v174
	v_exp_f32_e32 v141, v141
	v_sub_f32_e32 v140, v140, v174
	v_exp_f32_e32 v140, v140
	v_sub_f32_e32 v143, v143, v174
	v_sub_f32_e32 v138, v159, v174
	v_add_f32_e32 v159, 0, v139
	v_exp_f32_e32 v143, v143
	v_sub_f32_e32 v142, v142, v174
	v_add_f32_e32 v159, v172, v159
	v_exp_f32_e32 v142, v142
	v_sub_f32_e32 v137, v137, v174
	v_add_f32_e32 v159, v141, v159
	v_exp_f32_e32 v173, v137
	v_add_f32_e32 v159, v140, v159
	v_add_f32_e32 v159, v143, v159
	v_add_f32_e32 v159, v142, v159
	v_sub_f32_e32 v136, v136, v174
	v_add_f32_e32 v137, v173, v159
	v_exp_f32_e32 v159, v136
	v_exp_f32_e32 v136, v138
	v_cvt_pk_bf16_f32 v138, v143, v142
	v_add_f32_e32 v175, v159, v137
	v_fmac_f32_e32 v175, v158, v136
	v_mul_f32_e32 v26, v26, v136
	v_mul_f32_e32 v27, v27, v136
	v_mul_f32_e32 v24, v24, v136
	v_mul_f32_e32 v25, v25, v136
	v_mul_f32_e32 v30, v30, v136
	v_mul_f32_e32 v31, v31, v136
	v_mul_f32_e32 v28, v28, v136
	v_mul_f32_e32 v29, v29, v136
	v_mul_f32_e32 v34, v34, v136
	v_mul_f32_e32 v35, v35, v136
	v_mul_f32_e32 v32, v32, v136
	v_mul_f32_e32 v33, v33, v136
	v_mul_f32_e32 v38, v38, v136
	v_mul_f32_e32 v39, v39, v136
	v_mul_f32_e32 v36, v36, v136
	v_mul_f32_e32 v37, v37, v136
	v_cvt_pk_bf16_f32 v136, v139, v172
	v_cvt_pk_bf16_f32 v137, v141, v140
	v_cvt_pk_bf16_f32 v139, v173, v159
	v_mov_b32_e32 v158, v175
	v_mov_b32_e32 v159, v174
	v_mfma_f32_16x16x32_bf16 v[24:27], v[116:119], v[136:139], v[24:27]
	v_mfma_f32_16x16x32_bf16 v[28:31], v[112:115], v[136:139], v[28:31]
	v_mfma_f32_16x16x32_bf16 v[32:35], v[108:111], v[136:139], v[32:35]
	v_mfma_f32_16x16x32_bf16 v[36:39], v[104:107], v[136:139], v[36:39]
	s_and_b64 vcc, exec, s[4:5]
	s_cbranch_vccnz .LBB0_259

; template <int MODE>
; __device__ __forceinline__ void attn_wave(LAS unsigned char* lds, const bf16_t* qkv, bf16_t* Yout, const float* sinks, int wi) {
;     ...
;         const int k0 = kb * 32;
;         u32x4 vr[4];
; #pragma unroll
;         for (int i = 0; i < 4; ++i) { const int e = lane + 64 * i; vr[i] = *(const u32x4*)(vp + (size_t)(k0 + (e >> 3)) * QP + (e & 7) * 8); }
;         bf16x8 kf[2][2];
; #pragma unroll
;         for (int nt = 0; nt < 2; ++nt)
; #pragma unroll
;             for (int ks = 0; ks < 2; ++ks) kf[nt][ks] = *(const bf16x8*)(kp + (size_t)(k0 + 16 * nt + c) * QP + ks * 32 + g * 8);
; #pragma unroll
;         for (int i = 0; i < 4; ++i) { const int e = lane + 64 * i; *(LAS u32x4*)(Vs + (e >> 3) * KPB + (e & 7) * 16) = vr[i]; }
;         bf16x8 vfr[4];
;         { const LAS unsigned char* vb = Vs + (4 * g + (c >> 2)) * KPB + (c & 3) * 8;
; #pragma unroll
;           for (int dt = 0; dt < 4; ++dt) vfr[dt] = vfrag(vb + dt * 32); }
;         __builtin_amdgcn_sched_barrier(0);
; #pragma unroll
;         for (int qt = 0; qt < NQT; ++qt) {
;             bool live = (k0 <= q0 + QSTEP * qt + 15);
;             if (MODE == MODE_A) live = live && (q0 + QSTEP * qt - (k0 + 31) < 128);
;             if (MODE == MODE_C) { const bool dq = __all(carry[qt] < -150.1f); live = live && !dq; }
;             if (!live) continue;
;             f32x4 s[2];
; #pragma unroll
;             for (int nt = 0; nt < 2; ++nt) { f32x4 z = (f32x4){0.f, 0.f, 0.f, 0.f}; z = MFMA16(kf[nt][0], qf[qt][0], z); s[nt] = MFMA16(kf[nt][1], qf[qt][1], z); }
;             const int dbase = q0 + QSTEP * qt + c - k0 - 4 * g;
;             if (MODE == MODE_A) {
;                 float mx = -1e30f;
; #pragma unroll
;                 for (int nt = 0; nt < 2; ++nt)
; #pragma unroll
;                     for (int j = 0; j < 4; ++j) { const int dist = dbase - (16 * nt + j); const bool valid = (unsigned)dist < 128u;
;                         const float bias2 = lutp[qt * HSTEP * 128 + (dist & 127)];
;                         const float lg = valid ? (s[nt][j] * C1 + bias2) : -1e30f; s[nt][j] = lg; mx = fmaxf(mx, lg); }
;                 mx = fmaxf(mx, __shfl_xor(mx, 16)); mx = fmaxf(mx, __shfl_xor(mx, 32));
;                 const float mnew = fmaxf(mrun[qt], mx); const float alpha = __builtin_amdgcn_exp2f(mrun[qt] - mnew); mrun[qt] = mnew;
;                 float ps = 0.f;
; #pragma unroll
.LBB0_338:
	s_waitcnt vmcnt(0) lgkmcnt(0)
	ds_write_b128 v156, v[228:231]
	ds_write_b128 v156, v[232:235] offset:1152
	ds_write_b128 v156, v[236:239] offset:2304
	ds_write_b128 v156, v[240:243] offset:3456
	v_mov_b64_e32 v[132:133], v[190:191]
	v_mov_b64_e32 v[134:135], v[192:193]
	v_mov_b64_e32 v[136:137], v[194:195]
	v_mov_b64_e32 v[138:139], v[196:197]
	v_mov_b64_e32 v[128:129], v[198:199]
	v_mov_b64_e32 v[130:131], v[200:201]
	v_mov_b64_e32 v[124:125], v[202:203]
	v_mov_b64_e32 v[126:127], v[204:205]
	s_sub_i32 s32, s47, 32
	s_max_i32 s32, s32, 0
	v_add_u32_e32 v1, s32, v155
	v_add_u32_e32 v206, 8, v1
	v_mad_u64_u32 v[2:3], s[0:1], v1, s85, v[142:143]
	v_mad_u64_u32 v[232:233], s[0:1], v206, s85, v[142:143]
	global_load_dwordx4 v[228:231], v[2:3], off
	v_add_u32_e32 v2, 16, v1
	global_load_dwordx4 v[232:235], v[232:233], off
	v_add_u32_e32 v1, 24, v1
	v_mad_u64_u32 v[2:3], s[0:1], v2, s85, v[142:143]
	v_mad_u64_u32 v[240:241], s[0:1], v1, s85, v[142:143]
	global_load_dwordx4 v[236:239], v[2:3], off
	v_add_u32_e32 v1, s32, v153
	global_load_dwordx4 v[240:243], v[240:241], off
	v_mad_u64_u32 v[2:3], s[0:1], v1, s85, v[144:145]
	v_add_u32_e32 v1, 16, v1
	global_load_dwordx4 v[190:193], v[2:3], off
	global_load_dwordx4 v[194:197], v[2:3], off offset:64
	v_mad_u64_u32 v[2:3], s[0:1], v1, s85, v[144:145]
	s_nop 0
	global_load_dwordx4 v[198:201], v[2:3], off
	global_load_dwordx4 v[202:205], v[2:3], off offset:64
	ds_read_b64_tr_b16 v[112:113], v157
	ds_read_b64_tr_b16 v[108:109], v157 offset:32
	ds_read_b64_tr_b16 v[116:117], v157 offset:64
	ds_read_b64_tr_b16 v[120:121], v157 offset:96
	ds_read_b64_tr_b16 v[114:115], v157 offset:2304
	ds_read_b64_tr_b16 v[110:111], v157 offset:2336
	ds_read_b64_tr_b16 v[118:119], v157 offset:2368
	ds_read_b64_tr_b16 v[122:123], v157 offset:2400
	s_mov_b32 s10, 0xc316199a
	s_cmp_gt_u32 s47, s36
	v_cmp_gt_f32_e32 vcc, s10, v104
	s_cselect_b64 s[0:1], -1, 0
	s_cmp_eq_u64 vcc, exec
	s_cselect_b64 s[10:11], -1, 0
	v_add_u32_e32 v3, s47, v154
	s_or_b64 s[0:1], s[0:1], s[10:11]
	s_and_b64 vcc, exec, s[0:1]
	v_add_u32_e32 v163, 1, v3
	v_add_u32_e32 v162, 3, v3
	v_add_u32_e32 v161, 16, v3
	v_add_u32_e32 v160, 17, v3
	v_add_u32_e32 v158, 18, v3
	v_or_b32_e32 v2, 19, v3
	v_or_b32_e32 v159, 2, v3
	s_cbranch_vccnz .LBB0_340
	v_mfma_f32_16x16x32_bf16 v[164:167], v[132:135], v[40:43], 0
	s_mov_b32 s15, 0x3e38aa3b
	v_cmp_gt_u32_e32 vcc, v140, v163
	v_cmp_gt_u32_e64 s[0:1], v140, v159
	v_mfma_f32_16x16x32_bf16 v[164:167], v[136:139], v[44:47], v[164:167]
	v_cmp_gt_u32_e64 s[10:11], v151, v158
	v_mfma_f32_16x16x32_bf16 v[168:171], v[128:131], v[40:43], 0
	v_mfma_f32_16x16x32_bf16 v[168:171], v[124:127], v[44:47], v[168:171]
	s_nop 2
	v_mul_f32_e32 v172, 0x3e38aa3b, v165
	v_exp_f32_e64 v174, -|v172|
	v_mul_f32_e32 v1, 0x3e38aa3b, v164
	v_exp_f32_e64 v173, -|v1|
	v_max_f32_e32 v172, 0, v172
	v_add_f32_e32 v174, 1.0, v174
	v_log_f32_e32 v174, v174
	v_add_f32_e32 v173, 1.0, v173
	v_log_f32_e32 v173, v173
	v_max_f32_e32 v1, 0, v1
	v_add_f32_e32 v172, v172, v174
	v_fma_f32 v165, v165, s15, -v172
	v_cndmask_b32_e32 v182, v226, v165, vcc
	v_mul_f32_e32 v165, 0x3e38aa3b, v166
	v_add_f32_e32 v1, v1, v173
	v_exp_f32_e64 v173, -|v165|
	v_mul_f32_e32 v175, 0x3e38aa3b, v167
	v_exp_f32_e64 v176, -|v175|
	v_fma_f32 v177, v164, s15, -v1
	v_cndmask_b32_e64 v164, 0, -v172, vcc
	v_max_f32_e32 v172, 0, v165
	v_add_f32_e32 v165, 1.0, v173
	v_log_f32_e32 v174, v165
	v_add_f32_e32 v165, 1.0, v176
	v_max_f32_e32 v173, 0, v175
	v_mul_f32_e32 v175, 0x3e38aa3b, v168
	v_log_f32_e32 v165, v165
	v_exp_f32_e64 v178, -|v175|
	v_cmp_gt_u32_e32 vcc, v140, v162
	v_sub_f32_e32 v1, 0, v1
	v_add_f32_e32 v165, v173, v165
	v_add_f32_e32 v173, 1.0, v178
	v_log_f32_e32 v173, v173
	v_cndmask_b32_e64 v176, 0, -v165, vcc
	v_fma_f32 v165, v167, s15, -v165
	v_cndmask_b32_e32 v183, v226, v165, vcc
	v_max_f32_e32 v165, 0, v175
	v_mul_f32_e32 v167, 0x3e38aa3b, v169
	v_add_f32_e32 v165, v165, v173
	v_exp_f32_e64 v173, -|v167|
	v_fma_f32 v168, v168, s15, -v165
	v_cmp_gt_u32_e32 vcc, v140, v161
	v_max_f32_e32 v167, 0, v167
	v_sub_f32_e32 v165, 0, v165
	v_cndmask_b32_e32 v180, v226, v168, vcc
	v_add_f32_e32 v168, 1.0, v173
	v_log_f32_e32 v168, v168
	v_cndmask_b32_e32 v165, 0, v165, vcc
	v_cmp_gt_u32_e32 vcc, v140, v160
	v_add_f32_e32 v167, v167, v168
	v_mul_f32_e32 v168, 0x3e38aa3b, v170
	v_exp_f32_e64 v173, -|v168|
	v_cndmask_b32_e64 v181, 0, -v167, vcc
	v_fma_f32 v167, v169, s15, -v167
	v_cndmask_b32_e32 v184, v226, v167, vcc
	v_add_f32_e32 v167, 1.0, v173
	v_mul_f32_e32 v169, 0x3e38aa3b, v171
	v_log_f32_e32 v167, v167
	v_exp_f32_e64 v175, -|v169|
	v_max_f32_e32 v168, 0, v168
	v_cmp_lt_i32_e32 vcc, v223, v218
	v_add_f32_e32 v167, v168, v167
	v_add_f32_e32 v168, 1.0, v175
	v_log_f32_e32 v175, v168
	v_cndmask_b32_e32 v168, v217, v223, vcc
	v_cmp_lt_i32_e32 vcc, v224, v218
	v_lshlrev_b32_e32 v178, 2, v168
	v_max_f32_e32 v173, 0, v169
	v_cndmask_b32_e32 v168, v217, v224, vcc
	v_lshlrev_b32_e32 v185, 2, v168
	v_xor_b32_e32 v168, 48, v217
	v_cmp_lt_i32_e32 vcc, v168, v218
	v_add_f32_e32 v165, v181, v165
	v_fma_f32 v170, v170, s15, -v167
	v_cndmask_b32_e32 v168, v217, v168, vcc
	v_lshlrev_b32_e32 v186, 2, v168
	v_add_f32_e32 v168, v172, v174
	v_add_f32_e32 v169, v173, v175
	v_cmp_gt_u32_e32 vcc, v140, v3
	v_fma_f32 v166, v166, s15, -v168
	v_cndmask_b32_e64 v188, v226, v166, s[0:1]
	v_cndmask_b32_e32 v187, v226, v177, vcc
	v_cndmask_b32_e64 v167, 0, -v167, s[10:11]
	v_cndmask_b32_e32 v166, 0, v1, vcc
	v_cmp_gt_u32_e32 vcc, v151, v2
	v_add_f32_e32 v172, v166, v164
	v_add_f32_e32 v173, v167, v165
	v_cndmask_b32_e64 v174, 0, -v168, s[0:1]
	v_cndmask_b32_e64 v175, 0, -v169, vcc
	v_add_f32_e32 v172, v174, v172
	v_add_f32_e32 v173, v175, v173
	ds_bpermute_b32 v177, v178, v173
	v_fma_f32 v1, v171, s15, -v169
	ds_bpermute_b32 v169, v185, v173
	ds_bpermute_b32 v171, v186, v173
	v_cndmask_b32_e32 v165, v226, v1, vcc
	s_waitcnt lgkmcnt(2)
; __device__ __forceinline__ unsigned cvtpk(float lo, float hi) { f32x2 v = {lo, hi}; bf16x2_t b = __builtin_convertvector(v, bf16x2_t); return __builtin_bit_cast(unsigned, b); }
; #define MFMA16(a, b, c) __builtin_amdgcn_mfma_f32_16x16x32_bf16((a), (b), (c), 0, 0, 0)
; template <int MODE>
; __device__ __forceinline__ void attn_wave(LAS unsigned char* lds, const bf16_t* qkv, bf16_t* Yout, const float* sinks, int wi) {
;     ...
;                     for (int j = 0; j < 4; ++j) { const bool valid = (dbase - (16 * nt + j)) > 0; const float z = s[nt][j] * C1;
;                         const float e = __builtin_amdgcn_exp2f(-fabsf(z));
;                         const float sp = fmaxf(z, 0.f) + __builtin_amdgcn_logf(1.f + e);
;                         lk[nt][j] = valid ? -sp : 0.f; s[nt][j] = valid ? (z - sp) : -1e30f; c4[nt] += lk[nt][j]; } }
;                 float after = 0.f;
; #pragma unroll
;     ...
;                     const float v1 = __shfl_xor(c4[nt], 16), v2 = __shfl_xor(c4[nt], 32), v3 = __shfl_xor(c4[nt], 48);
;                     const float G = (((g ^ 1) > g) ? v1 : 0.f) + (((g ^ 2) > g) ? v2 : 0.f) + (((g ^ 3) > g) ? v3 : 0.f);
;                     const float T = c4[nt] + v1 + v2 + v3;
;                     float sfx = carry[qt] + after + G;
; #pragma unroll
;                     for (int j = 3; j >= 0; --j) { const float w = __builtin_amdgcn_exp2f(s[nt][j] + sfx); s[nt][j] = w; sfx += lk[nt][j]; }
;                     after += T;
;                 }
;                 carry[qt] += after;
;             }
;             u32x4 w; w.x = cvtpk(s[0][0], s[0][1]); w.y = cvtpk(s[0][2], s[0][3]); w.z = cvtpk(s[1][0], s[1][1]); w.w = cvtpk(s[1][2], s[1][3]);
;             const bf16x8 pb = __builtin_bit_cast(bf16x8, w);
; #pragma unroll
;             for (int dt = 0; dt < 4; ++dt) o[qt][dt] = MFMA16(vfr[dt], pb, o[qt][dt]);
	v_cndmask_b32_e64 v1, 0, v177, s[4:5]
	v_add_f32_e32 v172, v176, v172
	v_add_f32_e32 v173, v177, v173
	s_waitcnt lgkmcnt(1)
	v_cndmask_b32_e64 v166, 0, v169, s[6:7]
	ds_bpermute_b32 v168, v178, v172
	v_add_f32_e32 v179, v1, v166
	s_waitcnt lgkmcnt(1)
	v_cndmask_b32_e64 v1, 0, v171, s[8:9]
	v_mov_b32_e32 v178, v104
	v_add_f32_e32 v178, v178, v0
	v_add_f32_e32 v179, v179, v1
	v_cndmask_b32_e64 v189, v226, v170, s[10:11]
	v_add_f32_e32 v1, v178, v179
	v_add_f32_e32 v165, v1, v165
	v_add_f32_e32 v1, v1, v175
	ds_bpermute_b32 v170, v185, v172
	v_exp_f32_e32 v177, v165
	v_add_f32_e32 v165, v1, v189
	v_add_f32_e32 v1, v167, v1
	v_add_f32_e32 v166, v184, v1
	v_exp_f32_e32 v175, v166
	ds_bpermute_b32 v166, v186, v172
	s_waitcnt lgkmcnt(2)
	v_cndmask_b32_e64 v167, 0, v168, s[4:5]
	s_waitcnt lgkmcnt(1)
	v_cndmask_b32_e64 v178, 0, v170, s[6:7]
	v_add_f32_e32 v168, v172, v168
	v_add_f32_e32 v169, v173, v169
	v_add_f32_e32 v178, v167, v178
	v_add_f32_e32 v168, v168, v170
	v_add_f32_e32 v169, v169, v171
	v_mov_b32_e32 v167, v0
	v_add_f32_e32 v1, v181, v1
	s_waitcnt lgkmcnt(0)
	v_add_f32_e32 v168, v168, v166
	v_add_f32_e32 v169, v169, v167
	v_add_f32_e32 v1, v180, v1
	v_cndmask_b32_e64 v180, 0, v166, s[8:9]
	v_mov_b32_e32 v179, v104
	v_mov_b32_e32 v181, v169
	v_add_f32_e32 v166, v178, v180
	v_add_f32_e32 v167, v179, v181
	v_exp_f32_e32 v1, v1
	v_add_f32_e32 v166, v166, v167
	v_add_f32_e32 v167, v183, v166
	v_add_f32_e32 v166, v176, v166
	v_add_f32_e32 v170, v188, v166
	v_add_f32_e32 v166, v174, v166
	v_add_f32_e32 v164, v164, v166
	v_add_f32_e32 v171, v182, v166
	v_add_f32_e32 v164, v187, v164
	v_exp_f32_e32 v167, v167
	v_exp_f32_e32 v171, v171
	v_exp_f32_e32 v164, v164
	v_exp_f32_e32 v166, v170
	v_exp_f32_e32 v170, v165
	v_cvt_pk_bf16_f32 v164, v164, v171
	v_cvt_pk_bf16_f32 v165, v166, v167
	v_cvt_pk_bf16_f32 v166, v1, v175
	v_cvt_pk_bf16_f32 v167, v170, v177
	v_add_f32_e32 v1, v168, v169
	v_add_f32_e32 v104, v104, v1
	v_mfma_f32_16x16x32_bf16 v[100:103], v[112:115], v[164:167], v[100:103]
	v_mfma_f32_16x16x32_bf16 v[96:99], v[108:111], v[164:167], v[96:99]
	v_mfma_f32_16x16x32_bf16 v[92:95], v[116:119], v[164:167], v[92:95]
	v_mfma_f32_16x16x32_bf16 v[88:91], v[120:123], v[164:167], v[88:91]
.LBB0_340:
	s_mov_b32 s10, 0xc316199a
	s_cmp_gt_u32 s47, s44
	v_cmp_gt_f32_e32 vcc, s10, v105
	s_cselect_b64 s[0:1], -1, 0
	s_cmp_eq_u64 vcc, exec
	s_cselect_b64 s[10:11], -1, 0
	s_or_b64 s[0:1], s[0:1], s[10:11]
	s_and_b64 vcc, exec, s[0:1]
	s_cbranch_vccnz .LBB0_342
	v_mfma_f32_16x16x32_bf16 v[164:167], v[132:135], v[48:51], 0
	s_mov_b32 s15, 0x3e38aa3b
	v_cmp_gt_u32_e32 vcc, v146, v163
	v_cmp_gt_u32_e64 s[0:1], v146, v159
	v_mfma_f32_16x16x32_bf16 v[164:167], v[136:139], v[52:55], v[164:167]
	v_cmp_gt_u32_e64 s[10:11], v149, v158
	v_mfma_f32_16x16x32_bf16 v[168:171], v[128:131], v[48:51], 0
	v_mfma_f32_16x16x32_bf16 v[168:171], v[124:127], v[52:55], v[168:171]
	s_nop 2
	v_mul_f32_e32 v172, 0x3e38aa3b, v165
	v_exp_f32_e64 v174, -|v172|
	v_mul_f32_e32 v1, 0x3e38aa3b, v164
	v_exp_f32_e64 v173, -|v1|
	v_max_f32_e32 v172, 0, v172
	v_add_f32_e32 v174, 1.0, v174
	v_log_f32_e32 v174, v174
	v_add_f32_e32 v173, 1.0, v173
	v_log_f32_e32 v173, v173
	v_max_f32_e32 v1, 0, v1
	v_add_f32_e32 v172, v172, v174
	v_fma_f32 v165, v165, s15, -v172
	v_cndmask_b32_e32 v182, v226, v165, vcc
	v_mul_f32_e32 v165, 0x3e38aa3b, v166
	v_add_f32_e32 v1, v1, v173
	v_exp_f32_e64 v173, -|v165|
	v_mul_f32_e32 v175, 0x3e38aa3b, v167
	v_exp_f32_e64 v176, -|v175|
	v_fma_f32 v177, v164, s15, -v1
	v_cndmask_b32_e64 v164, 0, -v172, vcc
	v_max_f32_e32 v172, 0, v165
	v_add_f32_e32 v165, 1.0, v173
	v_log_f32_e32 v174, v165
	v_add_f32_e32 v165, 1.0, v176
	v_max_f32_e32 v173, 0, v175
	v_mul_f32_e32 v175, 0x3e38aa3b, v168
	v_log_f32_e32 v165, v165
	v_exp_f32_e64 v178, -|v175|
	v_cmp_gt_u32_e32 vcc, v146, v162
	v_sub_f32_e32 v1, 0, v1
	v_add_f32_e32 v165, v173, v165
	v_add_f32_e32 v173, 1.0, v178
	v_log_f32_e32 v173, v173
	v_cndmask_b32_e64 v176, 0, -v165, vcc
	v_fma_f32 v165, v167, s15, -v165
	v_cndmask_b32_e32 v183, v226, v165, vcc
	v_max_f32_e32 v165, 0, v175
	v_mul_f32_e32 v167, 0x3e38aa3b, v169
	v_add_f32_e32 v165, v165, v173
	v_exp_f32_e64 v173, -|v167|
	v_fma_f32 v168, v168, s15, -v165
	v_cmp_gt_u32_e32 vcc, v140, v3
	v_max_f32_e32 v167, 0, v167
	v_sub_f32_e32 v165, 0, v165
	v_cndmask_b32_e32 v180, v226, v168, vcc
	v_add_f32_e32 v168, 1.0, v173
	v_log_f32_e32 v168, v168
	v_cndmask_b32_e32 v165, 0, v165, vcc
	v_cmp_gt_u32_e32 vcc, v146, v160
	v_add_f32_e32 v167, v167, v168
	v_mul_f32_e32 v168, 0x3e38aa3b, v170
	v_exp_f32_e64 v173, -|v168|
	v_cndmask_b32_e64 v181, 0, -v167, vcc
	v_fma_f32 v167, v169, s15, -v167
	v_cndmask_b32_e32 v184, v226, v167, vcc
	v_add_f32_e32 v167, 1.0, v173
	v_mul_f32_e32 v169, 0x3e38aa3b, v171
	v_log_f32_e32 v167, v167
	v_exp_f32_e64 v175, -|v169|
	v_max_f32_e32 v168, 0, v168
	v_cmp_lt_i32_e32 vcc, v223, v218
	v_add_f32_e32 v167, v168, v167
	v_add_f32_e32 v168, 1.0, v175
	v_log_f32_e32 v175, v168
	v_cndmask_b32_e32 v168, v217, v223, vcc
	v_cmp_lt_i32_e32 vcc, v224, v218
	v_lshlrev_b32_e32 v178, 2, v168
	v_max_f32_e32 v173, 0, v169
	v_cndmask_b32_e32 v168, v217, v224, vcc
	v_lshlrev_b32_e32 v185, 2, v168
	v_xor_b32_e32 v168, 48, v217
	v_cmp_lt_i32_e32 vcc, v168, v218
	v_add_f32_e32 v165, v181, v165
	v_fma_f32 v170, v170, s15, -v167
	v_cndmask_b32_e32 v168, v217, v168, vcc
	v_lshlrev_b32_e32 v186, 2, v168
	v_add_f32_e32 v168, v172, v174
	v_add_f32_e32 v169, v173, v175
	v_cmp_gt_u32_e32 vcc, v146, v3
	v_fma_f32 v166, v166, s15, -v168
	v_cndmask_b32_e64 v188, v226, v166, s[0:1]
	v_cndmask_b32_e32 v187, v226, v177, vcc
	v_cndmask_b32_e64 v167, 0, -v167, s[10:11]
	v_cndmask_b32_e32 v166, 0, v1, vcc
	v_cmp_gt_u32_e32 vcc, v149, v2
	v_add_f32_e32 v172, v166, v164
	v_add_f32_e32 v173, v167, v165
	v_cndmask_b32_e64 v174, 0, -v168, s[0:1]
	v_cndmask_b32_e64 v175, 0, -v169, vcc
	v_add_f32_e32 v172, v174, v172
	v_add_f32_e32 v173, v175, v173
	ds_bpermute_b32 v177, v178, v173
	v_fma_f32 v1, v171, s15, -v169
	ds_bpermute_b32 v169, v185, v173
	ds_bpermute_b32 v171, v186, v173
	v_cndmask_b32_e32 v165, v226, v1, vcc
	s_waitcnt lgkmcnt(2)
; __device__ __forceinline__ unsigned cvtpk(float lo, float hi) { f32x2 v = {lo, hi}; bf16x2_t b = __builtin_convertvector(v, bf16x2_t); return __builtin_bit_cast(unsigned, b); }
; #define MFMA16(a, b, c) __builtin_amdgcn_mfma_f32_16x16x32_bf16((a), (b), (c), 0, 0, 0)
; template <int MODE>
; __device__ __forceinline__ void attn_wave(LAS unsigned char* lds, const bf16_t* qkv, bf16_t* Yout, const float* sinks, int wi) {
;     ...
;                     for (int j = 0; j < 4; ++j) { const bool valid = (dbase - (16 * nt + j)) > 0; const float z = s[nt][j] * C1;
;                         const float e = __builtin_amdgcn_exp2f(-fabsf(z));
;                         const float sp = fmaxf(z, 0.f) + __builtin_amdgcn_logf(1.f + e);
;                         lk[nt][j] = valid ? -sp : 0.f; s[nt][j] = valid ? (z - sp) : -1e30f; c4[nt] += lk[nt][j]; } }
;                 float after = 0.f;
; #pragma unroll
;     ...
;                     const float v1 = __shfl_xor(c4[nt], 16), v2 = __shfl_xor(c4[nt], 32), v3 = __shfl_xor(c4[nt], 48);
;                     const float G = (((g ^ 1) > g) ? v1 : 0.f) + (((g ^ 2) > g) ? v2 : 0.f) + (((g ^ 3) > g) ? v3 : 0.f);
;                     const float T = c4[nt] + v1 + v2 + v3;
;                     float sfx = carry[qt] + after + G;
; #pragma unroll
;                     for (int j = 3; j >= 0; --j) { const float w = __builtin_amdgcn_exp2f(s[nt][j] + sfx); s[nt][j] = w; sfx += lk[nt][j]; }
;                     after += T;
;                 }
;                 carry[qt] += after;
;             }
;             u32x4 w; w.x = cvtpk(s[0][0], s[0][1]); w.y = cvtpk(s[0][2], s[0][3]); w.z = cvtpk(s[1][0], s[1][1]); w.w = cvtpk(s[1][2], s[1][3]);
;             const bf16x8 pb = __builtin_bit_cast(bf16x8, w);
; #pragma unroll
;             for (int dt = 0; dt < 4; ++dt) o[qt][dt] = MFMA16(vfr[dt], pb, o[qt][dt]);
	v_cndmask_b32_e64 v1, 0, v177, s[4:5]
	v_add_f32_e32 v172, v176, v172
	v_add_f32_e32 v173, v177, v173
	s_waitcnt lgkmcnt(1)
	v_cndmask_b32_e64 v166, 0, v169, s[6:7]
	ds_bpermute_b32 v168, v178, v172
	v_add_f32_e32 v179, v1, v166
	s_waitcnt lgkmcnt(1)
	v_cndmask_b32_e64 v1, 0, v171, s[8:9]
	v_mov_b32_e32 v178, v105
	v_add_f32_e32 v178, v178, v0
	v_add_f32_e32 v179, v179, v1
	v_cndmask_b32_e64 v189, v226, v170, s[10:11]
	v_add_f32_e32 v1, v178, v179
	v_add_f32_e32 v165, v1, v165
	v_add_f32_e32 v1, v1, v175
	ds_bpermute_b32 v170, v185, v172
	v_exp_f32_e32 v177, v165
	v_add_f32_e32 v165, v1, v189
	v_add_f32_e32 v1, v167, v1
	v_add_f32_e32 v166, v184, v1
	v_exp_f32_e32 v175, v166
	ds_bpermute_b32 v166, v186, v172
	s_waitcnt lgkmcnt(2)
	v_cndmask_b32_e64 v167, 0, v168, s[4:5]
	s_waitcnt lgkmcnt(1)
	v_cndmask_b32_e64 v178, 0, v170, s[6:7]
	v_add_f32_e32 v168, v172, v168
	v_add_f32_e32 v169, v173, v169
	v_add_f32_e32 v178, v167, v178
	v_add_f32_e32 v168, v168, v170
	v_add_f32_e32 v169, v169, v171
	v_mov_b32_e32 v167, v0
	v_add_f32_e32 v1, v181, v1
	s_waitcnt lgkmcnt(0)
	v_add_f32_e32 v168, v168, v166
	v_add_f32_e32 v169, v169, v167
	v_add_f32_e32 v1, v180, v1
	v_cndmask_b32_e64 v180, 0, v166, s[8:9]
	v_mov_b32_e32 v179, v105
	v_mov_b32_e32 v181, v169
	v_add_f32_e32 v166, v178, v180
	v_add_f32_e32 v167, v179, v181
	v_exp_f32_e32 v1, v1
	v_add_f32_e32 v166, v166, v167
	v_add_f32_e32 v167, v183, v166
	v_add_f32_e32 v166, v176, v166
	v_add_f32_e32 v170, v188, v166
	v_add_f32_e32 v166, v174, v166
	v_add_f32_e32 v164, v164, v166
	v_add_f32_e32 v171, v182, v166
	v_add_f32_e32 v164, v187, v164
	v_exp_f32_e32 v167, v167
	v_exp_f32_e32 v171, v171
	v_exp_f32_e32 v164, v164
	v_exp_f32_e32 v166, v170
	v_exp_f32_e32 v170, v165
	v_cvt_pk_bf16_f32 v164, v164, v171
	v_cvt_pk_bf16_f32 v165, v166, v167
	v_cvt_pk_bf16_f32 v166, v1, v175
	v_cvt_pk_bf16_f32 v167, v170, v177
	v_add_f32_e32 v1, v168, v169
	v_add_f32_e32 v105, v105, v1
	v_mfma_f32_16x16x32_bf16 v[84:87], v[112:115], v[164:167], v[84:87]
	v_mfma_f32_16x16x32_bf16 v[80:83], v[108:111], v[164:167], v[80:83]
	v_mfma_f32_16x16x32_bf16 v[76:79], v[116:119], v[164:167], v[76:79]
	v_mfma_f32_16x16x32_bf16 v[68:71], v[120:123], v[164:167], v[68:71]
.LBB0_342:
	s_mov_b32 s10, 0xc316199a
	s_cmp_gt_u32 s47, s45
	v_cmp_gt_f32_e32 vcc, s10, v106
	s_cselect_b64 s[0:1], -1, 0
	s_cmp_eq_u64 vcc, exec
	s_cselect_b64 s[10:11], -1, 0
	s_or_b64 s[0:1], s[0:1], s[10:11]
	s_and_b64 vcc, exec, s[0:1]
	s_cbranch_vccnz .LBB0_344
	v_mfma_f32_16x16x32_bf16 v[164:167], v[132:135], v[56:59], 0
	s_mov_b32 s15, 0x3e38aa3b
	v_cmp_gt_u32_e32 vcc, v148, v163
	v_cmp_gt_u32_e64 s[0:1], v148, v159
	v_mfma_f32_16x16x32_bf16 v[164:167], v[136:139], v[60:63], v[164:167]
	v_cmp_gt_u32_e64 s[10:11], v147, v158
	v_mfma_f32_16x16x32_bf16 v[168:171], v[128:131], v[56:59], 0
	v_mfma_f32_16x16x32_bf16 v[168:171], v[124:127], v[60:63], v[168:171]
	s_nop 2
	v_mul_f32_e32 v172, 0x3e38aa3b, v165
	v_exp_f32_e64 v174, -|v172|
	v_mul_f32_e32 v1, 0x3e38aa3b, v164
	v_exp_f32_e64 v173, -|v1|
	v_max_f32_e32 v172, 0, v172
	v_add_f32_e32 v174, 1.0, v174
	v_log_f32_e32 v174, v174
	v_add_f32_e32 v173, 1.0, v173
	v_log_f32_e32 v173, v173
	v_max_f32_e32 v1, 0, v1
	v_add_f32_e32 v172, v172, v174
	v_fma_f32 v165, v165, s15, -v172
	v_cndmask_b32_e32 v182, v226, v165, vcc
	v_mul_f32_e32 v165, 0x3e38aa3b, v166
	v_add_f32_e32 v1, v1, v173
	v_exp_f32_e64 v173, -|v165|
	v_mul_f32_e32 v175, 0x3e38aa3b, v167
	v_exp_f32_e64 v176, -|v175|
	v_fma_f32 v177, v164, s15, -v1
	v_cndmask_b32_e64 v164, 0, -v172, vcc
	v_max_f32_e32 v172, 0, v165
	v_add_f32_e32 v165, 1.0, v173
	v_log_f32_e32 v174, v165
	v_add_f32_e32 v165, 1.0, v176
	v_max_f32_e32 v173, 0, v175
	v_mul_f32_e32 v175, 0x3e38aa3b, v168
	v_log_f32_e32 v165, v165
	v_exp_f32_e64 v178, -|v175|
	v_cmp_gt_u32_e32 vcc, v148, v162
	v_sub_f32_e32 v1, 0, v1
	v_add_f32_e32 v165, v173, v165
	v_add_f32_e32 v173, 1.0, v178
	v_log_f32_e32 v173, v173
	v_cndmask_b32_e64 v176, 0, -v165, vcc
	v_fma_f32 v165, v167, s15, -v165
	v_cndmask_b32_e32 v183, v226, v165, vcc
	v_max_f32_e32 v165, 0, v175
	v_mul_f32_e32 v167, 0x3e38aa3b, v169
	v_add_f32_e32 v165, v165, v173
	v_exp_f32_e64 v173, -|v167|
	v_fma_f32 v168, v168, s15, -v165
	v_cmp_gt_u32_e32 vcc, v148, v161
	v_max_f32_e32 v167, 0, v167
	v_sub_f32_e32 v165, 0, v165
	v_cndmask_b32_e32 v180, v226, v168, vcc
	v_add_f32_e32 v168, 1.0, v173
	v_log_f32_e32 v168, v168
	v_cndmask_b32_e32 v165, 0, v165, vcc
	v_cmp_gt_u32_e32 vcc, v148, v160
	v_add_f32_e32 v167, v167, v168
	v_mul_f32_e32 v168, 0x3e38aa3b, v170
	v_exp_f32_e64 v173, -|v168|
	v_cndmask_b32_e64 v181, 0, -v167, vcc
	v_fma_f32 v167, v169, s15, -v167
	v_cndmask_b32_e32 v184, v226, v167, vcc
	v_add_f32_e32 v167, 1.0, v173
	v_mul_f32_e32 v169, 0x3e38aa3b, v171
	v_log_f32_e32 v167, v167
	v_exp_f32_e64 v175, -|v169|
	v_max_f32_e32 v168, 0, v168
	v_cmp_lt_i32_e32 vcc, v223, v218
	v_add_f32_e32 v167, v168, v167
	v_add_f32_e32 v168, 1.0, v175
	v_log_f32_e32 v175, v168
	v_cndmask_b32_e32 v168, v217, v223, vcc
	v_cmp_lt_i32_e32 vcc, v224, v218
	v_lshlrev_b32_e32 v178, 2, v168
	v_max_f32_e32 v173, 0, v169
	v_cndmask_b32_e32 v168, v217, v224, vcc
	v_lshlrev_b32_e32 v185, 2, v168
	v_xor_b32_e32 v168, 48, v217
	v_cmp_lt_i32_e32 vcc, v168, v218
	v_add_f32_e32 v165, v181, v165
	v_fma_f32 v170, v170, s15, -v167
	v_cndmask_b32_e32 v168, v217, v168, vcc
	v_lshlrev_b32_e32 v186, 2, v168
	v_add_f32_e32 v168, v172, v174
	v_add_f32_e32 v169, v173, v175
	v_cmp_gt_u32_e32 vcc, v148, v3
	v_fma_f32 v166, v166, s15, -v168
	v_cndmask_b32_e64 v188, v226, v166, s[0:1]
	v_cndmask_b32_e32 v187, v226, v177, vcc
	v_cndmask_b32_e64 v167, 0, -v167, s[10:11]
	v_cndmask_b32_e32 v166, 0, v1, vcc
	v_cmp_gt_u32_e32 vcc, v147, v2
	v_add_f32_e32 v172, v166, v164
	v_add_f32_e32 v173, v167, v165
	v_cndmask_b32_e64 v174, 0, -v168, s[0:1]
	v_cndmask_b32_e64 v175, 0, -v169, vcc
	v_add_f32_e32 v172, v174, v172
	v_add_f32_e32 v173, v175, v173
	ds_bpermute_b32 v177, v178, v173
	v_fma_f32 v1, v171, s15, -v169
	ds_bpermute_b32 v169, v185, v173
	ds_bpermute_b32 v171, v186, v173
	v_cndmask_b32_e32 v165, v226, v1, vcc
	s_waitcnt lgkmcnt(2)
; __device__ __forceinline__ unsigned cvtpk(float lo, float hi) { f32x2 v = {lo, hi}; bf16x2_t b = __builtin_convertvector(v, bf16x2_t); return __builtin_bit_cast(unsigned, b); }
; #define MFMA16(a, b, c) __builtin_amdgcn_mfma_f32_16x16x32_bf16((a), (b), (c), 0, 0, 0)
; template <int MODE>
; __device__ __forceinline__ void attn_wave(LAS unsigned char* lds, const bf16_t* qkv, bf16_t* Yout, const float* sinks, int wi) {
;     ...
;                     for (int j = 0; j < 4; ++j) { const bool valid = (dbase - (16 * nt + j)) > 0; const float z = s[nt][j] * C1;
;                         const float e = __builtin_amdgcn_exp2f(-fabsf(z));
;                         const float sp = fmaxf(z, 0.f) + __builtin_amdgcn_logf(1.f + e);
;                         lk[nt][j] = valid ? -sp : 0.f; s[nt][j] = valid ? (z - sp) : -1e30f; c4[nt] += lk[nt][j]; } }
;                 float after = 0.f;
; #pragma unroll
;     ...
;                     const float v1 = __shfl_xor(c4[nt], 16), v2 = __shfl_xor(c4[nt], 32), v3 = __shfl_xor(c4[nt], 48);
;                     const float G = (((g ^ 1) > g) ? v1 : 0.f) + (((g ^ 2) > g) ? v2 : 0.f) + (((g ^ 3) > g) ? v3 : 0.f);
;                     const float T = c4[nt] + v1 + v2 + v3;
;                     float sfx = carry[qt] + after + G;
; #pragma unroll
;                     for (int j = 3; j >= 0; --j) { const float w = __builtin_amdgcn_exp2f(s[nt][j] + sfx); s[nt][j] = w; sfx += lk[nt][j]; }
;                     after += T;
;                 }
;                 carry[qt] += after;
;             }
;             u32x4 w; w.x = cvtpk(s[0][0], s[0][1]); w.y = cvtpk(s[0][2], s[0][3]); w.z = cvtpk(s[1][0], s[1][1]); w.w = cvtpk(s[1][2], s[1][3]);
;             const bf16x8 pb = __builtin_bit_cast(bf16x8, w);
; #pragma unroll
;             for (int dt = 0; dt < 4; ++dt) o[qt][dt] = MFMA16(vfr[dt], pb, o[qt][dt]);
	v_cndmask_b32_e64 v1, 0, v177, s[4:5]
	v_add_f32_e32 v172, v176, v172
	v_add_f32_e32 v173, v177, v173
	s_waitcnt lgkmcnt(1)
	v_cndmask_b32_e64 v166, 0, v169, s[6:7]
	ds_bpermute_b32 v168, v178, v172
	v_add_f32_e32 v179, v1, v166
	s_waitcnt lgkmcnt(1)
	v_cndmask_b32_e64 v1, 0, v171, s[8:9]
	v_mov_b32_e32 v178, v106
	v_add_f32_e32 v178, v178, v0
	v_add_f32_e32 v179, v179, v1
	v_cndmask_b32_e64 v189, v226, v170, s[10:11]
	v_add_f32_e32 v1, v178, v179
	v_add_f32_e32 v165, v1, v165
	v_add_f32_e32 v1, v1, v175
	ds_bpermute_b32 v170, v185, v172
	v_exp_f32_e32 v177, v165
	v_add_f32_e32 v165, v1, v189
	v_add_f32_e32 v1, v167, v1
	v_add_f32_e32 v166, v184, v1
	v_exp_f32_e32 v175, v166
	ds_bpermute_b32 v166, v186, v172
	s_waitcnt lgkmcnt(2)
	v_cndmask_b32_e64 v167, 0, v168, s[4:5]
	s_waitcnt lgkmcnt(1)
	v_cndmask_b32_e64 v178, 0, v170, s[6:7]
	v_add_f32_e32 v168, v172, v168
	v_add_f32_e32 v169, v173, v169
	v_add_f32_e32 v178, v167, v178
	v_add_f32_e32 v168, v168, v170
	v_add_f32_e32 v169, v169, v171
	v_mov_b32_e32 v167, v0
	v_add_f32_e32 v1, v181, v1
	s_waitcnt lgkmcnt(0)
	v_add_f32_e32 v168, v168, v166
	v_add_f32_e32 v169, v169, v167
	v_add_f32_e32 v1, v180, v1
	v_cndmask_b32_e64 v180, 0, v166, s[8:9]
	v_mov_b32_e32 v179, v106
	v_mov_b32_e32 v181, v169
	v_add_f32_e32 v166, v178, v180
	v_add_f32_e32 v167, v179, v181
	v_exp_f32_e32 v1, v1
	v_add_f32_e32 v166, v166, v167
	v_add_f32_e32 v167, v183, v166
	v_add_f32_e32 v166, v176, v166
	v_add_f32_e32 v170, v188, v166
	v_add_f32_e32 v166, v174, v166
	v_add_f32_e32 v164, v164, v166
	v_add_f32_e32 v171, v182, v166
	v_add_f32_e32 v164, v187, v164
	v_exp_f32_e32 v167, v167
	v_exp_f32_e32 v171, v171
	v_exp_f32_e32 v164, v164
	v_exp_f32_e32 v166, v170
	v_exp_f32_e32 v170, v165
	v_cvt_pk_bf16_f32 v164, v164, v171
	v_cvt_pk_bf16_f32 v165, v166, v167
	v_cvt_pk_bf16_f32 v166, v1, v175
	v_cvt_pk_bf16_f32 v167, v170, v177
	v_add_f32_e32 v1, v168, v169
	v_add_f32_e32 v106, v106, v1
	v_mfma_f32_16x16x32_bf16 v[36:39], v[112:115], v[164:167], v[36:39]
	v_mfma_f32_16x16x32_bf16 v[32:35], v[108:111], v[164:167], v[32:35]
	v_mfma_f32_16x16x32_bf16 v[28:31], v[116:119], v[164:167], v[28:31]
	v_mfma_f32_16x16x32_bf16 v[24:27], v[120:123], v[164:167], v[24:27]
; #define MFMA16(a, b, c) __builtin_amdgcn_mfma_f32_16x16x32_bf16((a), (b), (c), 0, 0, 0)
; template <int MODE>
; __device__ __forceinline__ void attn_wave(LAS unsigned char* lds, const bf16_t* qkv, bf16_t* Yout, const float* sinks, int wi) {
;     ...
;             bool live = (k0 <= q0 + QSTEP * qt + 15);
;             if (MODE == MODE_A) live = live && (q0 + QSTEP * qt - (k0 + 31) < 128);
;             if (MODE == MODE_C) { const bool dq = __all(carry[qt] < -150.1f); live = live && !dq; }
;             if (!live) continue;
;             f32x4 s[2];
; #pragma unroll
;             for (int nt = 0; nt < 2; ++nt) { f32x4 z = (f32x4){0.f, 0.f, 0.f, 0.f}; z = MFMA16(kf[nt][0], qf[qt][0], z); s[nt] = MFMA16(kf[nt][1], qf[qt][1], z); }
;             const int dbase = q0 + QSTEP * qt + c - k0 - 4 * g;
;             if (MODE == MODE_A) {
;                 float mx = -1e30f;
; #pragma unroll
;                 for (int nt = 0; nt < 2; ++nt)
; #pragma unroll
;                     for (int j = 0; j < 4; ++j) { const int dist = dbase - (16 * nt + j); const bool valid = (unsigned)dist < 128u;
;                         const float bias2 = lutp[qt * HSTEP * 128 + (dist & 127)];
;                         const float lg = valid ? (s[nt][j] * C1 + bias2) : -1e30f; s[nt][j] = lg; mx = fmaxf(mx, lg); }
;                 mx = fmaxf(mx, __shfl_xor(mx, 16)); mx = fmaxf(mx, __shfl_xor(mx, 32));
;                 const float mnew = fmaxf(mrun[qt], mx); const float alpha = __builtin_amdgcn_exp2f(mrun[qt] - mnew); mrun[qt] = mnew;
;                 float ps = 0.f;
; #pragma unroll
;                 for (int nt = 0; nt < 2; ++nt)
; #pragma unroll
;                     for (int j = 0; j < 4; ++j) { const float p = __builtin_amdgcn_exp2f(s[nt][j] - mnew); s[nt][j] = p; ps += p; }
;                 lrun[qt] = lrun[qt] * alpha + ps;
; #pragma unroll
;                 for (int dt = 0; dt < 4; ++dt) o[qt][dt] = o[qt][dt] * alpha;
;             } else {
;                 float lk[2][4], c4[2];
; #pragma unroll
;                 for (int nt = 0; nt < 2; ++nt) { c4[nt] = 0.f;
; #pragma unroll
;                     for (int j = 0; j < 4; ++j) { const bool valid = (dbase - (16 * nt + j)) > 0; const float z = s[nt][j] * C1;
;                         const float e = __builtin_amdgcn_exp2f(-fabsf(z));
;                         const float sp = fmaxf(z, 0.f) + __builtin_amdgcn_logf(1.f + e);
.LBB0_344:
	s_mov_b32 s10, 0xc316199a
	s_cmp_gt_u32 s47, s46
	v_cmp_gt_f32_e32 vcc, s10, v107
	s_cselect_b64 s[0:1], -1, 0
	s_cmp_eq_u64 vcc, exec
	s_cselect_b64 s[10:11], -1, 0
	s_or_b64 s[0:1], s[0:1], s[10:11]
	s_and_b64 vcc, exec, s[0:1]
	s_cbranch_vccnz .LBB0_337
	v_mfma_f32_16x16x32_bf16 v[132:135], v[132:135], v[64:67], 0
	s_mov_b32 s15, 0x3e38aa3b
	v_cmp_gt_u32_e32 vcc, v150, v163
	v_cmp_gt_u32_e64 s[10:11], v141, v158
	v_mfma_f32_16x16x32_bf16 v[132:135], v[136:139], v[72:75], v[132:135]
	v_cmp_gt_u32_e64 s[0:1], v150, v159
	v_mfma_f32_16x16x32_bf16 v[128:131], v[128:131], v[64:67], 0
	v_mfma_f32_16x16x32_bf16 v[124:127], v[124:127], v[72:75], v[128:131]
	s_nop 2
	v_mul_f32_e32 v136, 0x3e38aa3b, v133
	v_exp_f32_e64 v138, -|v136|
	v_mul_f32_e32 v1, 0x3e38aa3b, v132
	v_exp_f32_e64 v137, -|v1|
	v_max_f32_e32 v129, 0, v136
	v_add_f32_e32 v138, 1.0, v138
	v_log_f32_e32 v128, v138
	v_add_f32_e32 v137, 1.0, v137
	v_log_f32_e32 v137, v137
	v_max_f32_e32 v1, 0, v1
	v_add_f32_e32 v129, v129, v128
	v_cndmask_b32_e64 v128, 0, -v129, vcc
	v_fma_f32 v129, v133, s15, -v129
	v_cndmask_b32_e32 v163, v226, v129, vcc
	v_mul_f32_e32 v129, 0x3e38aa3b, v134
	v_exp_f32_e64 v131, -|v129|
	v_mul_f32_e32 v133, 0x3e38aa3b, v135
	v_exp_f32_e64 v136, -|v133|
	v_add_f32_e32 v1, v1, v137
	v_max_f32_e32 v130, 0, v129
	v_add_f32_e32 v129, 1.0, v131
	v_fma_f32 v137, v132, s15, -v1
	v_log_f32_e32 v132, v129
	v_add_f32_e32 v129, 1.0, v136
	v_max_f32_e32 v131, 0, v133
	v_mul_f32_e32 v133, 0x3e38aa3b, v124
	v_log_f32_e32 v129, v129
	v_exp_f32_e64 v138, -|v133|
	v_cmp_gt_u32_e32 vcc, v150, v162
	v_sub_f32_e32 v1, 0, v1
	v_add_f32_e32 v129, v131, v129
	v_add_f32_e32 v131, 1.0, v138
	v_log_f32_e32 v131, v131
	v_cndmask_b32_e64 v136, 0, -v129, vcc
	v_fma_f32 v129, v135, s15, -v129
	v_cndmask_b32_e32 v162, v226, v129, vcc
	v_max_f32_e32 v129, 0, v133
	v_add_f32_e32 v129, v129, v131
	v_mul_f32_e32 v131, 0x3e38aa3b, v125
	v_exp_f32_e64 v133, -|v131|
	v_fma_f32 v124, v124, s15, -v129
	v_cmp_gt_u32_e32 vcc, v150, v161
	v_max_f32_e32 v131, 0, v131
	v_sub_f32_e32 v129, 0, v129
	v_cndmask_b32_e32 v138, v226, v124, vcc
	v_add_f32_e32 v124, 1.0, v133
	v_log_f32_e32 v124, v124
	v_cndmask_b32_e32 v129, 0, v129, vcc
	v_cmp_gt_u32_e32 vcc, v150, v160
	v_add_f32_e32 v124, v131, v124
	v_mul_f32_e32 v131, 0x3e38aa3b, v126
	v_exp_f32_e64 v133, -|v131|
	v_cndmask_b32_e64 v139, 0, -v124, vcc
	v_fma_f32 v124, v125, s15, -v124
	v_cndmask_b32_e32 v160, v226, v124, vcc
	v_add_f32_e32 v124, 1.0, v133
	v_max_f32_e32 v125, 0, v131
	v_mul_f32_e32 v131, 0x3e38aa3b, v127
	v_log_f32_e32 v124, v124
	v_exp_f32_e64 v133, -|v131|
	v_cmp_lt_i32_e32 vcc, v223, v218
	v_max_f32_e32 v131, 0, v131
	v_add_f32_e32 v135, v125, v124
	v_add_f32_e32 v124, 1.0, v133
	v_log_f32_e32 v133, v124
	v_cndmask_b32_e32 v124, v217, v223, vcc
	v_cmp_lt_i32_e32 vcc, v224, v218
	v_lshlrev_b32_e32 v161, 2, v124
	v_add_f32_e32 v129, v139, v129
	v_cndmask_b32_e32 v124, v217, v224, vcc
	v_lshlrev_b32_e32 v164, 2, v124
	v_xor_b32_e32 v124, 48, v217
	v_cmp_lt_i32_e32 vcc, v124, v218
	v_fma_f32 v126, v126, s15, -v135
	v_cndmask_b32_e64 v158, v226, v126, s[10:11]
	v_cndmask_b32_e32 v124, v217, v124, vcc
	v_lshlrev_b32_e32 v165, 2, v124
	v_cmp_gt_u32_e32 vcc, v150, v3
	v_add_f32_e32 v124, v130, v132
	v_add_f32_e32 v125, v131, v133
	v_cndmask_b32_e64 v131, 0, -v135, s[10:11]
	v_cndmask_b32_e32 v166, v226, v137, vcc
	v_fma_f32 v3, v134, s15, -v124
	v_cndmask_b32_e32 v130, 0, v1, vcc
	v_cmp_gt_u32_e32 vcc, v141, v2
	v_cndmask_b32_e64 v159, v226, v3, s[0:1]
	v_add_f32_e32 v132, v130, v128
	v_add_f32_e32 v133, v131, v129
	v_cndmask_b32_e64 v3, 0, -v125, vcc
	v_cndmask_b32_e64 v2, 0, -v124, s[0:1]
	v_add_f32_e32 v132, v2, v132
	v_add_f32_e32 v133, v3, v133
	ds_bpermute_b32 v137, v161, v133
	v_fma_f32 v1, v127, s15, -v125
	ds_bpermute_b32 v125, v164, v133
	ds_bpermute_b32 v127, v165, v133
	v_cndmask_b32_e32 v129, v226, v1, vcc
	s_waitcnt lgkmcnt(2)
	v_cndmask_b32_e64 v1, 0, v137, s[4:5]
	v_mov_b32_e32 v134, v107
	s_waitcnt lgkmcnt(1)
	v_cndmask_b32_e64 v126, 0, v125, s[6:7]
	v_add_f32_e32 v135, v1, v126
	s_waitcnt lgkmcnt(0)
	v_cndmask_b32_e64 v1, 0, v127, s[8:9]
	v_add_f32_e32 v134, v134, v0
	v_add_f32_e32 v135, v135, v1
	v_add_f32_e32 v132, v136, v132
	v_add_f32_e32 v133, v137, v133
	v_add_f32_e32 v1, v134, v135
	v_add_f32_e32 v129, v1, v129
	v_add_f32_e32 v1, v1, v3
	ds_bpermute_b32 v124, v161, v132
	ds_bpermute_b32 v126, v164, v132
	v_add_f32_e32 v3, v1, v158
	v_add_f32_e32 v1, v131, v1
	v_add_f32_e32 v130, v160, v1
	v_exp_f32_e32 v137, v130
	ds_bpermute_b32 v130, v165, v132
	s_waitcnt lgkmcnt(2)
	v_cndmask_b32_e64 v131, 0, v124, s[4:5]
	s_waitcnt lgkmcnt(1)
	v_cndmask_b32_e64 v134, 0, v126, s[6:7]
	v_add_f32_e32 v124, v132, v124
	v_add_f32_e32 v125, v133, v125
	v_add_f32_e32 v1, v139, v1
	v_add_f32_e32 v134, v131, v134
	v_add_f32_e32 v124, v124, v126
	v_add_f32_e32 v125, v125, v127
	v_mov_b32_e32 v131, v0
	v_add_f32_e32 v1, v138, v1
	s_waitcnt lgkmcnt(0)
	v_cndmask_b32_e64 v138, 0, v130, s[8:9]
	v_add_f32_e32 v130, v124, v130
	v_add_f32_e32 v131, v125, v131
	v_mov_b32_e32 v135, v107
	v_mov_b32_e32 v139, v131
	v_add_f32_e32 v124, v134, v138
	v_add_f32_e32 v125, v135, v139
	v_exp_f32_e32 v129, v129
	v_add_f32_e32 v124, v124, v125
	v_add_f32_e32 v125, v162, v124
	v_add_f32_e32 v124, v136, v124
	v_add_f32_e32 v2, v2, v124
	v_add_f32_e32 v126, v159, v124
	v_add_f32_e32 v124, v163, v2
	v_add_f32_e32 v2, v128, v2
	v_add_f32_e32 v2, v166, v2
	v_exp_f32_e32 v125, v125
	v_exp_f32_e32 v124, v124
	v_exp_f32_e32 v2, v2
	v_exp_f32_e32 v126, v126
	v_exp_f32_e32 v1, v1
	v_exp_f32_e32 v3, v3
	v_cvt_pk_bf16_f32 v124, v2, v124
	v_cvt_pk_bf16_f32 v125, v126, v125
	v_cvt_pk_bf16_f32 v126, v1, v137
	v_cvt_pk_bf16_f32 v127, v3, v129
	v_add_f32_e32 v1, v130, v131
	v_add_f32_e32 v107, v107, v1
	v_mfma_f32_16x16x32_bf16 v[20:23], v[112:115], v[124:127], v[20:23]
	v_mfma_f32_16x16x32_bf16 v[16:19], v[108:111], v[124:127], v[16:19]
	v_mfma_f32_16x16x32_bf16 v[12:15], v[116:119], v[124:127], v[12:15]
	v_mfma_f32_16x16x32_bf16 v[8:11], v[120:123], v[124:127], v[8:11]
	s_branch .LBB0_337
